# baseline (speedup 1.0000x reference)
.LBB0_35:
	s_or_b64 exec, exec, s[2:3]
	v_readlane_b32 s2, v254, 52
	v_readlane_b32 s3, v254, 53
	s_waitcnt vmcnt(0)
	v_lshl_add_u64 v[0:1], s[2:3], 2, v[0:1]
	global_atomic_add v[0:1], v149, off
	buffer_inv sc1
